# weight prep in gate/up phases: last item round moved to the six-tile workgroups (they used to do none and finished ~17us earlier)
# baseline (speedup 1.0000x reference)
.LBB0_923:
	s_and_b64 vcc, exec, s[6:7]
	s_cbranch_vccz .LBB0_1018
	s_lshl_b32 s0, s31, 3
	s_add_i32 s4, s0, 0xfffffc00
	v_add_u32_e32 v43, s4, v5
	s_and_b64 s[6:7], s[12:13], exec
	s_movk_i32 s4, 0x2100
	s_cselect_b32 s4, s4, 0x3180
	s_and_b64 s[6:7], s[16:17], exec
	s_cselect_b32 s28, 0xb00, s4
	s_and_b64 s[6:7], s[12:13], exec
	s_movk_i32 s4, 0x4200
	s_cselect_b32 s4, 0x3180, s4
	s_and_b64 s[6:7], s[16:17], exec
	s_cselect_b32 s8, 0x2100, s4
	s_and_b64 s[6:7], s[12:13], exec
	s_cselect_b32 s4, 0x4800, 0
	s_and_b64 s[6:7], s[16:17], exec
	s_cselect_b32 s4, 0x4200, s4
	s_and_b64 s[6:7], s[12:13], exec
	s_cselect_b32 s9, 0x5000, 0
	s_and_b64 s[6:7], s[16:17], exec
	s_cselect_b32 s6, 0x4800, s9
	s_sub_i32 s29, s8, s28
	s_sub_i32 s36, s6, s4
	v_mov_b32_e32 v42, v156
	s_add_i32 s36, s36, s29
	s_add_i32 s9, s36, 0x3ff
	s_lshr_b32 s9, s9, 10
	s_add_i32 s9, s9, -1
	s_lshl_b32 s9, s9, 10
	s_cmp_eq_u32 s9, 0
	s_cselect_b32 s9, s36, s9
	s_cmpk_lt_i32 s31, 0x80
	s_cbranch_scc1 .Lpb_six
	s_mov_b32 s36, s9
	s_branch .Lpb_go
.Lpb_six:
	s_add_i32 s0, s0, s9
	v_add_u32_e32 v43, s0, v5
	s_addk_i32 s0, 0x400
.Lpb_go:
	v_cmp_gt_i32_e32 vcc, s36, v43
	v_and_b32_e32 v3, 63, v42
	s_and_saveexec_b64 s[16:17], vcc
	s_cbranch_execz .LBB0_1004
	v_lshlrev_b32_e32 v0, 8, v42
	v_and_b32_e32 v0, 0xffffc000, v0
	v_add_u32_e32 v1, 0, v0
	v_lshrrev_b32_e32 v0, 5, v3
	v_and_b32_e32 v2, 31, v42
	v_mul_u32_u24_e32 v4, 0x84, v0
	v_lshlrev_b32_e32 v6, 2, v2
	v_add3_u32 v44, v1, v4, v6
	v_lshlrev_b32_e32 v4, 3, v3
	v_and_b32_e32 v4, 56, v4
	v_lshlrev_b32_e32 v158, 1, v4
	v_lshrrev_b32_e32 v107, 3, v3
	v_lshl_add_u64 v[14:15], s[90:91], 0, v[158:159]
	s_mov_b64 s[6:7], 0x1080000
	v_mul_u32_u24_e32 v8, 0x84, v4
	v_lshl_add_u64 v[6:7], v[14:15], 0, s[6:7]
	v_lshlrev_b32_e32 v9, 2, v107
	s_mov_b64 s[6:7], 0x1680000
	v_add3_u32 v108, v1, v8, v9
	v_lshl_add_u64 v[8:9], v[14:15], 0, s[6:7]
	s_mov_b64 s[6:7], 0x6080000
	v_lshl_add_u64 v[10:11], v[14:15], 0, s[6:7]
	s_mov_b64 s[6:7], 0x5e80000
	v_lshl_add_u64 v[12:13], v[14:15], 0, s[6:7]
	s_mov_b64 s[6:7], 0x5c80000
	v_add_u32_e32 v16, s0, v5
	s_sub_i32 s37, s4, s29
	v_or_b32_e32 v45, 2, v0
	v_add_u32_e32 v46, 0x108, v44
	v_or_b32_e32 v47, 4, v0
	v_add_u32_e32 v48, 0x210, v44
	v_or_b32_e32 v49, 6, v0
	v_add_u32_e32 v50, 0x318, v44
	v_or_b32_e32 v51, 8, v0
	v_add_u32_e32 v52, 0x420, v44
	v_or_b32_e32 v53, 10, v0
	v_add_u32_e32 v54, 0x528, v44
	v_or_b32_e32 v55, 12, v0
	v_add_u32_e32 v56, 0x630, v44
	v_or_b32_e32 v57, 14, v0
	v_add_u32_e32 v58, 0x738, v44
	v_or_b32_e32 v59, 16, v0
	v_add_u32_e32 v60, 0x840, v44
	v_or_b32_e32 v61, 18, v0
	v_add_u32_e32 v62, 0x948, v44
	v_or_b32_e32 v63, 20, v0
	v_add_u32_e32 v64, 0xa50, v44
	v_or_b32_e32 v65, 22, v0
	v_add_u32_e32 v66, 0xb58, v44
	v_or_b32_e32 v67, 24, v0
	v_add_u32_e32 v68, 0xc60, v44
	v_or_b32_e32 v69, 26, v0
	v_add_u32_e32 v70, 0xd68, v44
	v_or_b32_e32 v71, 28, v0
	v_add_u32_e32 v72, 0xe70, v44
	v_or_b32_e32 v73, 30, v0
	v_add_u32_e32 v74, 0xf78, v44
	v_or_b32_e32 v75, 32, v0
	v_add_u32_e32 v76, 0x1080, v44
	v_or_b32_e32 v77, 34, v0
	v_add_u32_e32 v78, 0x1188, v44
	v_or_b32_e32 v79, 36, v0
	v_add_u32_e32 v80, 0x1290, v44
	v_or_b32_e32 v81, 38, v0
	v_add_u32_e32 v82, 0x1398, v44
	v_or_b32_e32 v83, 40, v0
	v_add_u32_e32 v84, 0x14a0, v44
	v_or_b32_e32 v85, 42, v0
	v_add_u32_e32 v86, 0x15a8, v44
	v_or_b32_e32 v87, 44, v0
	v_add_u32_e32 v88, 0x16b0, v44
	v_or_b32_e32 v89, 46, v0
	v_add_u32_e32 v90, 0x17b8, v44
	v_or_b32_e32 v91, 48, v0
	v_add_u32_e32 v92, 0x18c0, v44
	v_or_b32_e32 v93, 50, v0
	v_add_u32_e32 v94, 0x19c8, v44
	v_or_b32_e32 v95, 52, v0
	v_add_u32_e32 v96, 0x1ad0, v44
	v_or_b32_e32 v97, 54, v0
	v_add_u32_e32 v98, 0x1bd8, v44
	v_or_b32_e32 v99, 56, v0
	v_add_u32_e32 v100, 0x1ce0, v44
	v_or_b32_e32 v101, 58, v0
	v_add_u32_e32 v102, 0x1de8, v44
	v_or_b32_e32 v103, 60, v0
	v_add_u32_e32 v104, 0x1ef0, v44
	v_or_b32_e32 v105, 62, v0
	v_add_u32_e32 v106, 0x1ff8, v44
	v_or_b32_e32 v109, 8, v107
	v_or_b32_e32 v110, 16, v107
	v_or_b32_e32 v111, 24, v107
	v_lshl_add_u64 v[14:15], v[14:15], 0, s[6:7]
	v_mov_b32_e32 v1, v159
	v_add_u32_e32 v112, 0xffffb200, v16
	s_mov_b64 s[18:19], 0
	s_branch .LBB0_931

.LBB0_1004:
	s_or_b64 exec, exec, s[16:17]
	s_and_b64 vcc, exec, s[12:13]
	s_movk_i32 s36, 0x7f
	s_cmpk_lt_i32 s79, 0x80
	s_cbranch_scc1 .LBB0_1018
	s_cbranch_vccz .LBB0_1018
	v_lshl_or_b32 v0, v43, 6, v3
	s_mov_b32 s0, 0x40000
	v_cmp_gt_i32_e32 vcc, s0, v0
	s_and_saveexec_b64 s[12:13], vcc
	s_cbranch_execz .LBB0_1017
	v_and_b32_e32 v1, 15, v42
	v_lshlrev_b32_e32 v1, 2, v1
	global_load_dword v2, v1, s[92:93] offset:184
	s_lshl_b32 s0, s31, 9
	s_add_i32 s0, s0, 0xfffe0000
	v_lshl_add_u32 v1, v5, 6, s0
	v_or_b32_e32 v3, v1, v3
	v_ashrrev_i32_e32 v1, 31, v0
	v_lshl_add_u64 v[0:1], v[0:1], 3, s[90:91]
	s_mov_b64 s[6:7], 0xfc00004
	v_lshl_add_u64 v[0:1], v[0:1], 0, s[6:7]
	s_mov_b64 s[16:17], 0
	s_waitcnt vmcnt(0)
	s_branch .LBB0_1008
